# FFN-up: workgroups of an XCD start the tile loop with distinct small delays so tile sharers do not miss L2 together
# speedup vs baseline: 1.0473x; 1.0163x over previous
.LBB0_934:
	s_and_b64 vcc, exec, s[0:1]
	s_cbranch_vccz .LBB0_951
	s_cmpk_gt_i32 s9, 0xaff
	v_readfirstlane_b32 s1, v198
	s_cbranch_scc1 .LBB0_951
	s_lshr_b32 s98, s9, 3
	s_and_b32 s98, s98, 31
	s_cmp_eq_u32 s98, 0
	s_cbranch_scc1 .Lskew_done
.Lskew_loop:
	s_sleep 1
	s_sub_i32 s98, s98, 1
	s_cmp_lg_u32 s98, 0
	s_cbranch_scc1 .Lskew_loop
.Lskew_done:
	v_lshlrev_b32_e32 v0, 4, v198
	s_waitcnt lgkmcnt(0)
	v_add_u32_e32 v1, 0x2000, v0
	v_ashrrev_i32_e32 v2, 31, v1
	v_lshrrev_b32_e32 v2, 22, v2
	v_add_u32_e32 v2, v1, v2
	v_ashrrev_i32_e32 v8, 10, v2
	v_mul_i32_i24_e32 v2, 0x400, v8
	v_sub_u32_e32 v1, v1, v2
	v_lshrrev_b32_e32 v2, 4, v1
	v_bitop3_b32 v1, v2, v1, 32 bitop3:0x6c
	v_ashrrev_i32_e32 v2, 31, v1
	v_lshrrev_b32_e32 v2, 26, v2
	v_readlane_b32 s0, v255, 32
	v_add_u32_e32 v2, v1, v2
	v_lshlrev_b32_e32 v3, 3, v8
	s_cmp_eq_u32 s0, 1
	v_ashrrev_i32_e32 v9, 6, v2
	v_and_b32_e32 v3, -16, v3
	s_cselect_b32 s0, 0, 0x2000000
	v_add_u32_e32 v3, v9, v3
	s_add_u32 s16, s91, s0
	v_and_b32_e32 v4, 3, v9
	s_mov_b32 s0, 0x1fffe0
	v_lshrrev_b32_e32 v5, 2, v3
	v_lshlrev_b32_e32 v6, 1, v3
	v_and_b32_e32 v2, 0xc0, v2
	v_and_or_b32 v4, v3, s0, v4
	v_and_b32_e32 v5, 4, v5
	v_and_b32_e32 v6, 24, v6
	v_sub_u32_e32 v1, v1, v2
	v_or3_b32 v4, v4, v5, v6
	v_lshlrev_b32_e32 v5, 5, v8
	v_ashrrev_i16_sdwa v1, v252, sext(v1) dst_sel:DWORD dst_unused:UNUSED_PAD src0_sel:DWORD src1_sel:BYTE_0
	v_and_b32_e32 v5, 32, v5
	v_bfe_i32 v10, v1, 0, 16
	v_add_lshl_u32 v1, v5, v10, 1
	v_lshl_add_u32 v154, v4, 11, v1
	v_lshl_add_u32 v156, v3, 11, v1
	v_bfe_i32 v1, v198, 27, 1
	v_lshrrev_b32_e32 v1, 22, v1
	v_add_u32_e32 v1, v0, v1
	v_and_b32_e32 v1, 0xfffffc00, v1
	v_sub_u32_e32 v0, v0, v1
	v_lshrrev_b32_e32 v1, 4, v0
	v_ashrrev_i32_e32 v2, 31, v198
	v_bitop3_b32 v0, v1, v0, 32 bitop3:0x6c
	v_lshrrev_b32_e32 v2, 26, v2
	v_ashrrev_i32_e32 v1, 31, v0
	v_add_u32_e32 v2, v198, v2
	v_lshrrev_b32_e32 v1, 26, v1
	v_ashrrev_i32_e32 v12, 6, v2
	v_add_u32_e32 v1, v0, v1
	v_lshlrev_b32_e32 v2, 3, v12
	v_ashrrev_i32_e32 v11, 6, v1
	v_and_b32_e32 v2, -16, v2
	s_addc_u32 s38, s90, 0
	v_add_u32_e32 v2, v11, v2
	v_and_b32_e32 v3, 3, v11
	s_ashr_i32 s45, s9, 31
	v_and_or_b32 v3, v2, s0, v3
	s_lshr_b32 s0, s45, 29
	s_add_i32 s0, s9, s0
	s_ashr_i32 s8, s1, 6
	s_ashr_i32 s4, s0, 3
	s_and_b32 s0, s0, -8
	s_ashr_i32 s2, s1, 8
	s_lshl_b32 s39, s8, 10
	s_sub_i32 s0, s9, s0
	s_cmp_lt_i32 s0, 0
	s_movk_i32 s5, 0x161
	s_cselect_b32 s5, s5, 0x160
	s_mul_i32 s0, s5, s0
	s_add_i32 s0, s0, s4
	s_mul_hi_i32 s4, s0, 0x2e8ba2e9
	s_lshr_b32 s5, s4, 31
	s_ashr_i32 s4, s4, 5
	s_add_i32 s4, s4, s5
	s_lshl_b32 s5, s4, 3
	s_mulk_i32 s4, 0xb0
	s_sub_i32 s4, s0, s4
	s_bfe_u32 s0, s4, 0x3001c
	s_add_i32 s6, s4, s0
	s_sext_i32_i16 s0, s6
	s_and_b32 s6, s6, 0xfff8
	s_sub_i32 s4, s4, s6
	s_sext_i32_i16 s4, s4
	v_lshrrev_b32_e32 v4, 2, v2
	v_lshlrev_b32_e32 v5, 1, v2
	v_and_b32_e32 v1, 0xc0, v1
	s_lshr_b32 s0, s0, 3
	s_add_i32 s4, s5, s4
	v_and_b32_e32 v4, 4, v4
	v_and_b32_e32 v5, 24, v5
	v_sub_u32_e32 v0, v0, v1
	s_ashr_i32 s5, s4, 31
	s_bfe_i64 s[14:15], s[0:1], 0x100000
	v_or3_b32 v3, v3, v4, v5
	v_lshlrev_b32_e32 v4, 5, v12
	v_ashrrev_i16_sdwa v0, v252, sext(v0) dst_sel:DWORD dst_unused:UNUSED_PAD src0_sel:DWORD src1_sel:BYTE_0
	s_lshl_b64 s[6:7], s[4:5], 19
	s_lshl_b64 s[14:15], s[14:15], 19
	v_and_b32_e32 v4, 32, v4
	v_bfe_i32 v13, v0, 0, 16
	s_add_u32 s66, s16, s14
	v_add_lshl_u32 v0, v4, v13, 1
	s_addc_u32 s67, s38, s15
	s_add_i32 s47, s39, 0
	v_lshl_add_u32 v96, v3, 11, v0
	s_add_i32 m0, s47, 0x10000
	v_lshl_add_u32 v158, v2, 11, v0
	global_load_lds_dwordx4 v96, s[66:67]
	s_add_i32 m0, s47, 0x12000
	s_add_u32 s14, s66, 0x40000
	global_load_lds_dwordx4 v154, s[66:67]
	s_addc_u32 s15, s67, 0
	s_add_i32 m0, s47, 0x14000
	v_mov_b32_e32 v155, v97
	global_load_lds_dwordx4 v96, s[14:15]
	s_add_i32 m0, s47, 0x16000
	s_add_u32 s42, s52, s6
	s_addc_u32 s43, s53, s7
	s_add_i32 s70, s47, 0x2000
	global_load_lds_dwordx4 v154, s[14:15]
	s_mov_b32 m0, s47
	s_add_u32 s6, s42, 0x40000
	global_load_lds_dwordx4 v158, s[42:43]
	s_mov_b32 m0, s70
	s_addc_u32 s7, s43, 0
	s_add_i32 s71, s47, 0x4000
	global_load_lds_dwordx4 v156, s[42:43]
	s_mov_b32 m0, s71
	s_add_i32 s72, s47, 0x6000
	global_load_lds_dwordx4 v158, s[6:7]
	s_mov_b32 m0, s72
	v_mov_b32_e32 v159, v97
	global_load_lds_dwordx4 v156, s[6:7]
	v_mov_b32_e32 v157, v97
	s_cmp_eq_u32 s2, 1
	v_lshl_add_u64 v[6:7], s[66:67], 0, v[96:97]
	v_lshl_add_u64 v[4:5], s[66:67], 0, v[154:155]
	v_lshl_add_u64 v[0:1], s[42:43], 0, v[158:159]
	s_cselect_b64 s[6:7], -1, 0
	s_cmp_lg_u32 s2, 1
	v_lshl_add_u64 v[2:3], s[42:43], 0, v[156:157]
	s_cbranch_scc1 .LBB0_938
	s_barrier
